# layer-0 bf16 output stores of the second tile's epilogue made write-through (sc1): full-line dwordx4 stores drain to HBM as issued, so the phase barrier's L2 write-back has little left to flush
# speedup vs baseline: 1.0134x; 1.0112x over previous
;     ...
;         const char* base = lds + cb * BUF;
;         bf16x8 af[MT], bfr[NT];
; #pragma unroll
;         for (int nt = 0; nt < NT; ++nt) {
;             const int br = BM + (nt / NTS) * (BN / NSEG) + wc * (NTS * 16) + (nt % NTS) * 16;
;             bfr[nt] = *(const bf16x8*)(base + (br + l15) * 64 + rsw);
;         }
; #pragma unroll
;         for (int mt = 0; mt < MT; ++mt) af[mt] = *(const bf16x8*)(base + (wr * WM + mt * 16 + l15) * 64 + rsw);
;         constexpr int TOT = MT * NT, PER = (TOT + NIT - 1) / NIT;
; #pragma unroll
;         for (int part = 0; part < NIT; ++part) {
; #pragma unroll
;             for (int q = 0; q < PER; ++q) {
;                 const int idx = part * PER + q;
;                 if (idx < TOT) {
;                     const int mt = idx / NT, nt = idx % NT;
;                     acc[mt][nt] = SWAP ? mfma16(bfr[nt], af[mt], acc[mt][nt]) : mfma16(af[mt], bfr[nt], acc[mt][nt]);
;                 }
; DI void unit_O(const Params& p, char* lds, int l, int tile, int glu_tiles, int tile_b) {
;     ...
;     const int xrot = (int)(((blockIdx.x >> 3) + (blockIdx.x & 7) * 4) & 31) * 4;
;     const bf16_t* xbres = WS_PTR(const bf16_t, OFF_XB1) + ((size_t)((tile >> 1) * 32) * 128 + (tile & 1) * 64) * 32;
;     auto issue_x = [&](int half) {
;         if (l == 0) {
; #pragma unroll 1
;             for (int i = 0; i < 16; ++i) {
;                 const int pc = (wid * 16 + i + xrot) & 127, row = pc >> 2, phys = (pc & 3) * 64 + lane, logical = phys ^ (row & 15);
;                 __builtin_amdgcn_global_load_lds((const unsigned*)(xres + (r0 + half * 32 + row) * 1024 + logical * 4), (unsigned*)(XR + pc * 1024 + lane * 16), 16, 0, 0);
;             }
;         } else {
; #pragma unroll 1
;             for (int i = 0; i < 8; ++i) {
;                 const int pc = (wid * 8 + i + (xrot >> 1)) & 63, kt = pc >> 1, sub = pc & 1;
;                 __builtin_amdgcn_global_load_lds((const unsigned*)(xbres + ((size_t)kt * 128 + half * 32) * 32 + sub * 512 + lane * 8), (unsigned*)(XR + pc * 1024 + lane * 16), 16, 0, 0);
;             }
;         }
;     };
;     issue_x(0);
;     {
;         const float* gsrc = (tid < 256) ? (p.ln_g + l * 1024 + tid * 4) : (p.ln_b + l * 1024 + (tid - 256) * 4);
;         *(f32x4*)(GB + tid * 4) = *(const f32x4*)gsrc;
;     }
;     float* xo = (l == 0) ? WS_PTR(float, OFF_X1) : p.out;
;     bf16_t* xbo = WS_PTR(bf16_t, OFF_XB1);
.Lpo2_join:
.LBB0_382:
	s_waitcnt vmcnt(0)
	v_add_u32_e32 v0, 0x11000, v140
	s_barrier
	v_add_u32_e32 v134, v0, v141
	v_add_u32_e32 v0, v0, v139
	ds_read_b128 v[130:133], v134 offset:4096
	ds_read_b128 v[138:141], v0
	ds_read_b128 v[142:145], v134 offset:5120
	ds_read_b128 v[146:149], v0 offset:1024
	ds_read_b128 v[150:153], v134 offset:6144
	ds_read_b128 v[154:157], v134 offset:7168
	ds_read_b128 v[158:161], v134 offset:8192
	ds_read_b128 v[162:165], v134 offset:9216
	ds_read_b128 v[166:169], v134 offset:10240
	ds_read_b128 v[170:173], v134 offset:11264
	ds_read_b128 v[174:177], v0 offset:2048
	ds_read_b128 v[178:181], v0 offset:3072
	s_waitcnt lgkmcnt(0)
	v_mfma_f32_16x16x32_bf16 v[98:101], v[130:133], v[138:141], v[98:101]
	v_and_b32_e32 v197, 63, v136
	v_ashrrev_i32_e32 v236, 6, v136
	v_mfma_f32_16x16x32_bf16 v[94:97], v[142:145], v[138:141], v[94:97]
	v_mfma_f32_16x16x32_bf16 v[90:93], v[150:153], v[138:141], v[90:93]
	v_mfma_f32_16x16x32_bf16 v[86:89], v[154:157], v[138:141], v[86:89]
	v_mfma_f32_16x16x32_bf16 v[82:85], v[158:161], v[138:141], v[82:85]
	v_mfma_f32_16x16x32_bf16 v[78:81], v[162:165], v[138:141], v[78:81]
	v_mfma_f32_16x16x32_bf16 v[74:77], v[166:169], v[138:141], v[74:77]
	v_mfma_f32_16x16x32_bf16 v[70:73], v[170:173], v[138:141], v[70:73]
	v_mfma_f32_16x16x32_bf16 v[126:129], v[130:133], v[146:149], v[126:129]
	v_mfma_f32_16x16x32_bf16 v[122:125], v[142:145], v[146:149], v[122:125]
	v_mfma_f32_16x16x32_bf16 v[118:121], v[150:153], v[146:149], v[118:121]
	v_mfma_f32_16x16x32_bf16 v[114:117], v[154:157], v[146:149], v[114:117]
	v_mfma_f32_16x16x32_bf16 v[110:113], v[158:161], v[146:149], v[110:113]
	v_mfma_f32_16x16x32_bf16 v[106:109], v[162:165], v[146:149], v[106:109]
	v_mfma_f32_16x16x32_bf16 v[102:105], v[166:169], v[146:149], v[102:105]
	v_mfma_f32_16x16x32_bf16 v[66:69], v[170:173], v[146:149], v[66:69]
	v_mfma_f32_16x16x32_bf16 v[34:37], v[130:133], v[174:177], v[34:37]
	v_mfma_f32_16x16x32_bf16 v[30:33], v[142:145], v[174:177], v[30:33]
	v_mfma_f32_16x16x32_bf16 v[26:29], v[150:153], v[174:177], v[26:29]
	v_mfma_f32_16x16x32_bf16 v[22:25], v[154:157], v[174:177], v[22:25]
	v_mfma_f32_16x16x32_bf16 v[18:21], v[158:161], v[174:177], v[18:21]
	v_mfma_f32_16x16x32_bf16 v[14:17], v[162:165], v[174:177], v[14:17]
	v_mfma_f32_16x16x32_bf16 v[10:13], v[166:169], v[174:177], v[10:13]
	v_mfma_f32_16x16x32_bf16 v[6:9], v[170:173], v[174:177], v[6:9]
	v_mfma_f32_16x16x32_bf16 v[62:65], v[130:133], v[178:181], v[62:65]
	v_mfma_f32_16x16x32_bf16 v[58:61], v[142:145], v[178:181], v[58:61]
	v_mfma_f32_16x16x32_bf16 v[54:57], v[150:153], v[178:181], v[54:57]
	v_mfma_f32_16x16x32_bf16 v[50:53], v[154:157], v[178:181], v[50:53]
	v_mfma_f32_16x16x32_bf16 v[46:49], v[158:161], v[178:181], v[46:49]
	v_mfma_f32_16x16x32_bf16 v[42:45], v[162:165], v[178:181], v[42:45]
	v_mfma_f32_16x16x32_bf16 v[38:41], v[166:169], v[178:181], v[38:41]
	v_mfma_f32_16x16x32_bf16 v[2:5], v[170:173], v[178:181], v[2:5]
	s_barrier
	s_not_b64 s[6:7], s[10:11]
	v_and_b32_e32 v138, 15, v212
	v_bfe_u32 v139, v212, 4, 2
	v_lshrrev_b32_e32 v140, 6, v212
	v_and_b32_e32 v141, 63, v212
	v_readfirstlane_b32 s90, v140
	v_and_b32_e32 v142, 0xff, v212
	v_lshlrev_b32_e32 v142, 4, v142
	s_cmp_lt_u32 s90, 4
	s_cselect_b32 s92, s14, s12
	s_cselect_b32 s93, s15, s13
	s_nop 3
	global_load_dwordx4 v[176:179], v142, s[92:93]
	v_lshlrev_b32_e32 v143, 4, v212
	v_add_u32_e32 v143, 0x20000, v143
	v_lshlrev_b32_e32 v134, 6, v138
	v_add_u32_e32 v135, 0x22000, v134
	v_lshl_add_u32 v134, v140, 3, v135
	v_lshlrev_b32_e32 v136, 9, v140
	v_lshl_add_u32 v136, v139, 4, v136
	v_add_u32_e32 v136, 0x20000, v136
	s_cmp_lg_u64 s[10:11], 0
	s_cbranch_scc1 .Le2_l1
	s_lshl_b32 s40, s48, 18
	s_lshl_b32 s91, s90, 13
	s_add_u32 s96, s52, s40
	s_addc_u32 s97, s53, 0
	s_add_u32 s96, s96, s91
	s_addc_u32 s97, s97, 0
	s_lshl_b32 s40, s90, 1
	v_xor_b32_e32 v208, s40, v141
	v_lshlrev_b32_e32 v208, 4, v208
	s_add_u32 s40, s40, 1
	v_xor_b32_e32 v209, s40, v141
	v_lshlrev_b32_e32 v209, 4, v209
	v_lshlrev_b32_e32 v133, 12, v138
	v_lshl_add_u32 v133, v140, 9, v133
	v_add_u32_e32 v200, 0, v139
	v_xor_b32_e32 v200, v200, v138
	v_lshl_add_u32 v200, v200, 4, v133
	v_add_u32_e32 v204, 0x10000, v200
	v_add_u32_e32 v201, 4, v139
	v_xor_b32_e32 v201, v201, v138
	v_lshl_add_u32 v201, v201, 4, v133
	v_add_u32_e32 v205, 0x10000, v201
	v_add_u32_e32 v202, 8, v139
	v_xor_b32_e32 v202, v202, v138
	v_lshl_add_u32 v202, v202, 4, v133
	v_add_u32_e32 v206, 0x10000, v202
	v_add_u32_e32 v203, 12, v139
	v_xor_b32_e32 v203, v203, v138
	v_lshl_add_u32 v203, v203, 4, v133
	v_add_u32_e32 v207, 0x10000, v203
	v_and_b32_e32 v137, 1, v139
	v_lshlrev_b32_e32 v137, 5, v137
	v_lshrrev_b32_e32 v130, 1, v139
	v_lshl_or_b32 v137, v130, 4, v137
	v_lshl_or_b32 v137, v138, 6, v137
	v_lshl_or_b32 v137, v140, 15, v137
	s_lshr_b32 s40, s48, 1
	s_lshl_b32 s40, s40, 18
	s_and_b32 s46, s48, 1
	s_lshl_b32 s46, s46, 12
	s_add_u32 s40, s40, s46
	s_add_u32 s78, s56, s40
	s_addc_u32 s79, s57, 0
	s_add_u32 s92, s96, 0x0
	s_addc_u32 s93, s97, 0
	s_add_u32 s40, s91, 0x0
	s_mov_b32 m0, s40
	s_nop 0
	global_load_lds_dwordx4 v208, s[92:93]
	global_load_lds_dwordx4 v208, s[92:93] offset:1024
	global_load_lds_dwordx4 v208, s[92:93] offset:2048
	global_load_lds_dwordx4 v208, s[92:93] offset:3072
	s_add_u32 s92, s96, 0x1000
	s_addc_u32 s93, s97, 0
	s_add_u32 s40, s91, 0x1000
	s_mov_b32 m0, s40
	s_nop 0
	global_load_lds_dwordx4 v209, s[92:93]
	global_load_lds_dwordx4 v209, s[92:93] offset:1024
	global_load_lds_dwordx4 v209, s[92:93] offset:2048
	global_load_lds_dwordx4 v209, s[92:93] offset:3072
	s_add_u32 s92, s96, 0x10000
	s_addc_u32 s93, s97, 0
	s_add_u32 s40, s91, 0x10000
	s_mov_b32 m0, s40
	s_nop 0
	global_load_lds_dwordx4 v208, s[92:93]
	global_load_lds_dwordx4 v208, s[92:93] offset:1024
	global_load_lds_dwordx4 v208, s[92:93] offset:2048
	global_load_lds_dwordx4 v208, s[92:93] offset:3072
	s_add_u32 s92, s96, 0x11000
	s_addc_u32 s93, s97, 0
	s_add_u32 s40, s91, 0x11000
	s_mov_b32 m0, s40
	s_nop 0
	global_load_lds_dwordx4 v209, s[92:93]
	global_load_lds_dwordx4 v209, s[92:93] offset:1024
	global_load_lds_dwordx4 v209, s[92:93] offset:2048
	global_load_lds_dwordx4 v209, s[92:93] offset:3072
	s_waitcnt vmcnt(16)
	ds_write_b128 v143, v[176:179]
	s_waitcnt vmcnt(8) lgkmcnt(0)
	s_barrier
; DI float bf2f(unsigned b) { return __uint_as_float(b << 16); }
; DI void unit_O(const Params& p, char* lds, int l, int tile, int glu_tiles, int tile_b) {
;     ...
;         float s2[2], ss2[2];
; #pragma unroll
;         for (int mh = 0; mh < 2; ++mh) {
;             const int mt = half * 2 + mh, rl = mh * 16 + l15;
;             float s = 0.f, ss = 0.f;
; #pragma unroll
;             for (int nt = 0; nt < 8; ++nt) {
;                 f32x4 xr;
;                 if (l == 0) {
;                     const int chunk = wid * 32 + nt * 4 + quad;
;                     xr = *(const f32x4*)(XR + rl * 4096 + ((chunk ^ l15) << 4));
;                 } else {
;                     const u32x2 hb = *(const u32x2*)(XR + ((wid * 4 + (nt >> 1)) * 32 + rl) * 64 + (nt & 1) * 32 + quad * 8);
;                     xr = (f32x4){bf2f(hb[0] & 0xffffu), bf2f(hb[0] >> 16), bf2f(hb[1] & 0xffffu), bf2f(hb[1] >> 16)};
;                 }
; #pragma unroll
;                 for (int i = 0; i < 4; ++i) { const float v = acc[mt][nt][i] + DN_ALPHA * xr[i]; acc[mt][nt][i] = v; s += v; ss += v * v; }
;             }
;             s2[mh] = s; ss2[mh] = ss;
;         }
; #pragma unroll
;         for (int mh = 0; mh < 2; ++mh) { s2[mh] += __shfl_xor(s2[mh], 16); ss2[mh] += __shfl_xor(ss2[mh], 16); }
; #pragma unroll
;         for (int mh = 0; mh < 2; ++mh) { s2[mh] += __shfl_xor(s2[mh], 32); ss2[mh] += __shfl_xor(ss2[mh], 32); }
;         if (quad == 0) {
; #pragma unroll
;             for (int mh = 0; mh < 2; ++mh) *(f32x2*)&red[((mh * 16 + l15) * 8 + wid) * 2] = (f32x2){s2[mh], ss2[mh]};
;         }
;         __syncthreads();
;         if (half == 0) issue_x(1);
; #pragma unroll
;         for (int mh = 0; mh < 2; ++mh) {
;             const int mt = half * 2 + mh, rl = mh * 16 + l15, row = mt * 16 + l15;
;             float s = 0.f, ss = 0.f;
; #pragma unroll
;             for (int w = 0; w < 4; ++w) { const f32x4 v = *(const f32x4*)&red[rl * 16 + 4 * w]; s += v[0] + v[2]; ss += v[1] + v[3]; }
;             const float mu = s * (1.f / 1024.f);
;             const float var = ss * (1.f / 1024.f) - mu * mu;
;             const float rs = rsqrtf(var + LN_EPS);
	ds_read_b128 v[144:147], v200
	ds_read_b128 v[148:151], v201
	ds_read_b128 v[152:155], v202
	ds_read_b128 v[156:159], v203
	ds_read_b128 v[160:163], v200 offset:256
	ds_read_b128 v[164:167], v201 offset:256
	ds_read_b128 v[168:171], v202 offset:256
	ds_read_b128 v[172:175], v203 offset:256
	s_waitcnt lgkmcnt(7)
	v_fmac_f32_e32 v98, s58, v144
	v_fmac_f32_e32 v99, s58, v145
	v_fmac_f32_e32 v100, s58, v146
	v_fmac_f32_e32 v101, s58, v147
	v_mov_b32_e32 v196, v98
	v_mul_f32_e32 v197, v98, v98
	v_mov_b32_e32 v130, v99
	v_mul_f32_e32 v142, v99, v99
	v_add_f32_e32 v196, v196, v100
	v_fmac_f32_e32 v197, v100, v100
	v_add_f32_e32 v130, v130, v101
	v_fmac_f32_e32 v142, v101, v101
	s_waitcnt lgkmcnt(6)
	v_fmac_f32_e32 v94, s58, v148
	v_fmac_f32_e32 v95, s58, v149
	v_fmac_f32_e32 v96, s58, v150
	v_fmac_f32_e32 v97, s58, v151
	v_add_f32_e32 v196, v196, v94
	v_fmac_f32_e32 v197, v94, v94
	v_add_f32_e32 v130, v130, v95
	v_fmac_f32_e32 v142, v95, v95
	v_add_f32_e32 v196, v196, v96
	v_fmac_f32_e32 v197, v96, v96
	v_add_f32_e32 v130, v130, v97
	v_fmac_f32_e32 v142, v97, v97
	s_waitcnt lgkmcnt(5)
	v_fmac_f32_e32 v90, s58, v152
	v_fmac_f32_e32 v91, s58, v153
	v_fmac_f32_e32 v92, s58, v154
	v_fmac_f32_e32 v93, s58, v155
	v_add_f32_e32 v196, v196, v90
	v_fmac_f32_e32 v197, v90, v90
	v_add_f32_e32 v130, v130, v91
	v_fmac_f32_e32 v142, v91, v91
	v_add_f32_e32 v196, v196, v92
	v_fmac_f32_e32 v197, v92, v92
	v_add_f32_e32 v130, v130, v93
	v_fmac_f32_e32 v142, v93, v93
	s_waitcnt lgkmcnt(4)
	v_fmac_f32_e32 v86, s58, v156
	v_fmac_f32_e32 v87, s58, v157
	v_fmac_f32_e32 v88, s58, v158
	v_fmac_f32_e32 v89, s58, v159
	v_add_f32_e32 v196, v196, v86
	v_fmac_f32_e32 v197, v86, v86
	v_add_f32_e32 v130, v130, v87
	v_fmac_f32_e32 v142, v87, v87
	v_add_f32_e32 v196, v196, v88
	v_fmac_f32_e32 v197, v88, v88
	v_add_f32_e32 v130, v130, v89
	v_fmac_f32_e32 v142, v89, v89
	s_waitcnt lgkmcnt(3)
	v_fmac_f32_e32 v82, s58, v160
	v_fmac_f32_e32 v83, s58, v161
	v_fmac_f32_e32 v84, s58, v162
	v_fmac_f32_e32 v85, s58, v163
	v_add_f32_e32 v196, v196, v82
	v_fmac_f32_e32 v197, v82, v82
	v_add_f32_e32 v130, v130, v83
	v_fmac_f32_e32 v142, v83, v83
	v_add_f32_e32 v196, v196, v84
	v_fmac_f32_e32 v197, v84, v84
	v_add_f32_e32 v130, v130, v85
	v_fmac_f32_e32 v142, v85, v85
	s_waitcnt lgkmcnt(2)
	v_fmac_f32_e32 v78, s58, v164
	v_fmac_f32_e32 v79, s58, v165
	v_fmac_f32_e32 v80, s58, v166
	v_fmac_f32_e32 v81, s58, v167
	v_add_f32_e32 v196, v196, v78
	v_fmac_f32_e32 v197, v78, v78
	v_add_f32_e32 v130, v130, v79
	v_fmac_f32_e32 v142, v79, v79
	v_add_f32_e32 v196, v196, v80
	v_fmac_f32_e32 v197, v80, v80
	v_add_f32_e32 v130, v130, v81
	v_fmac_f32_e32 v142, v81, v81
	s_waitcnt lgkmcnt(1)
	v_fmac_f32_e32 v74, s58, v168
	v_fmac_f32_e32 v75, s58, v169
	v_fmac_f32_e32 v76, s58, v170
	v_fmac_f32_e32 v77, s58, v171
	v_add_f32_e32 v196, v196, v74
	v_fmac_f32_e32 v197, v74, v74
	v_add_f32_e32 v130, v130, v75
	v_fmac_f32_e32 v142, v75, v75
	v_add_f32_e32 v196, v196, v76
	v_fmac_f32_e32 v197, v76, v76
	v_add_f32_e32 v130, v130, v77
	v_fmac_f32_e32 v142, v77, v77
	s_waitcnt lgkmcnt(0)
	v_fmac_f32_e32 v70, s58, v172
	v_fmac_f32_e32 v71, s58, v173
	v_fmac_f32_e32 v72, s58, v174
	v_fmac_f32_e32 v73, s58, v175
	v_add_f32_e32 v196, v196, v70
	v_fmac_f32_e32 v197, v70, v70
	v_add_f32_e32 v130, v130, v71
	v_fmac_f32_e32 v142, v71, v71
	v_add_f32_e32 v196, v196, v72
	v_fmac_f32_e32 v197, v72, v72
	v_add_f32_e32 v130, v130, v73
	v_fmac_f32_e32 v142, v73, v73
	v_add_f32_e32 v196, v196, v130
	v_add_f32_e32 v197, v197, v142
	v_mov_b32_e32 v198, v196
	v_mov_b32_e32 v199, v197
	s_nop 1
	v_permlane16_swap_b32 v198, v196
	v_permlane16_swap_b32 v199, v197
	v_add_f32_e32 v196, v196, v198
	v_add_f32_e32 v197, v197, v199
	v_mov_b32_e32 v198, v196
	v_mov_b32_e32 v199, v197
	s_nop 1
	v_permlane32_swap_b32 v198, v196
	v_permlane32_swap_b32 v199, v197
	v_add_f32_e32 v196, v196, v198
	v_add_f32_e32 v197, v197, v199
	s_mov_b64 exec, 0xffff
	ds_write_b64 v134, v[196:197]
	s_mov_b64 exec, -1
	s_waitcnt lgkmcnt(0)
	s_barrier
	s_add_u32 s92, s96, 0x20000
	s_addc_u32 s93, s97, 0
	s_add_u32 s40, s91, 0x0
	s_mov_b32 m0, s40
	s_nop 0
	global_load_lds_dwordx4 v208, s[92:93]
	global_load_lds_dwordx4 v208, s[92:93] offset:1024
	global_load_lds_dwordx4 v208, s[92:93] offset:2048
	global_load_lds_dwordx4 v208, s[92:93] offset:3072
	s_add_u32 s92, s96, 0x21000
	s_addc_u32 s93, s97, 0
	s_add_u32 s40, s91, 0x1000
	s_mov_b32 m0, s40
	s_nop 0
	global_load_lds_dwordx4 v209, s[92:93]
	global_load_lds_dwordx4 v209, s[92:93] offset:1024
	global_load_lds_dwordx4 v209, s[92:93] offset:2048
	global_load_lds_dwordx4 v209, s[92:93] offset:3072
	ds_read_b128 v[160:163], v135 offset:0
	ds_read_b128 v[164:167], v135 offset:16
	ds_read_b128 v[168:171], v135 offset:32
	ds_read_b128 v[172:175], v135 offset:48
	s_waitcnt lgkmcnt(0)
	v_add_f32_e32 v160, v160, v162
	v_add_f32_e32 v161, v161, v163
	v_add_f32_e32 v164, v164, v166
	v_add_f32_e32 v165, v165, v167
	v_add_f32_e32 v168, v168, v170
	v_add_f32_e32 v169, v169, v171
	v_add_f32_e32 v172, v172, v174
	v_add_f32_e32 v173, v173, v175
	v_add_f32_e32 v160, v160, v164
	v_add_f32_e32 v161, v161, v165
	v_add_f32_e32 v168, v168, v172
	v_add_f32_e32 v169, v169, v173
	v_add_f32_e32 v160, v160, v168
	v_add_f32_e32 v161, v161, v169
	v_mul_f32_e32 v192, 0x3a800000, v160
	v_mul_f32_e32 v193, 0x3a800000, v161
	v_fma_f32 v193, -v192, v192, v193
	v_add_f32_e32 v193, 0x3727c5ac, v193
	v_rsq_f32_e32 v193, v193
	s_nop 0
	s_add_u32 s94, s78, 0x0
	s_addc_u32 s95, s79, 0
	ds_read_b128 v[176:179], v136
	ds_read_b128 v[180:183], v136 offset:4096
	ds_read_b128 v[184:187], v136 offset:64
	ds_read_b128 v[188:191], v136 offset:4160
	s_waitcnt lgkmcnt(2)
; DI unsigned pk2(float lo, float hi) { const f32x2 v = {lo, hi}; const bf16x2_t b = __builtin_convertvector(v, bf16x2_t); return __builtin_bit_cast(unsigned, b); }
; DI size_t xb_off(int tok, int col) { return ((size_t)(((tok >> 7) * 32 + (col >> 5)) * 128 + (tok & 127))) * 32 + (col & 31); }
; DI void unit_O(const Params& p, char* lds, int l, int tile, int glu_tiles, int tile_b) {
;     ...
;             float* orow = xo + (r0 + row) * 1024 + wid * 128 + quad * 4;
;             bf16_t* brow = xbo + xb_off((int)r0 + row, wid * 128) + quad * 4;
;             const float* gp = GB + wid * 128 + quad * 4;
; #pragma unroll
;             for (int nt = 0; nt < 8; ++nt) {
;                 const f32x4 g = *(const f32x4*)(gp + nt * 16), bb = *(const f32x4*)(gp + 1024 + nt * 16);
;                 f32x4 o;
; #pragma unroll
;                 for (int i = 0; i < 4; ++i) o[i] = (acc[mt][nt][i] - mu) * rs * g[i] + bb[i];
;                 if (l == 0) *(u32x2*)(brow + (nt >> 1) * 4096 + (nt & 1) * 16) = (u32x2){pk2(o[0], o[1]), pk2(o[2], o[3])};
;                 else *(f32x4*)(orow + nt * 16) = o;
;             }
	v_sub_f32_e32 v98, v98, v192
	v_mul_f32_e32 v98, v98, v193
	v_fma_f32 v98, v176, v98, v180
	v_sub_f32_e32 v99, v99, v192
	v_mul_f32_e32 v99, v99, v193
	v_fma_f32 v99, v177, v99, v181
	v_sub_f32_e32 v100, v100, v192
	v_mul_f32_e32 v100, v100, v193
	v_fma_f32 v100, v178, v100, v182
	v_sub_f32_e32 v101, v101, v192
	v_mul_f32_e32 v101, v101, v193
	v_fma_f32 v101, v179, v101, v183
	v_cvt_pk_bf16_f32 v144, v98, v99
	v_cvt_pk_bf16_f32 v145, v100, v101
	ds_read_b128 v[176:179], v136 offset:128
	ds_read_b128 v[180:183], v136 offset:4224
	s_waitcnt lgkmcnt(2)
	v_sub_f32_e32 v94, v94, v192
	v_mul_f32_e32 v94, v94, v193
	v_fma_f32 v94, v184, v94, v188
	v_sub_f32_e32 v95, v95, v192
	v_mul_f32_e32 v95, v95, v193
	v_fma_f32 v95, v185, v95, v189
	v_sub_f32_e32 v96, v96, v192
	v_mul_f32_e32 v96, v96, v193
	v_fma_f32 v96, v186, v96, v190
	v_sub_f32_e32 v97, v97, v192
	v_mul_f32_e32 v97, v97, v193
	v_fma_f32 v97, v187, v97, v191
	v_cvt_pk_bf16_f32 v146, v94, v95
	v_cvt_pk_bf16_f32 v147, v96, v97
	s_nop 1
	v_permlane16_swap_b32 v144, v146
	v_permlane16_swap_b32 v145, v147
	global_store_dwordx4 v137, v[144:147], s[94:95] sc1
	s_add_u32 s94, s94, 0x2000
	s_addc_u32 s95, s95, 0
	ds_read_b128 v[184:187], v136 offset:192
	ds_read_b128 v[188:191], v136 offset:4288
	s_waitcnt lgkmcnt(2)
	v_sub_f32_e32 v90, v90, v192
	v_mul_f32_e32 v90, v90, v193
	v_fma_f32 v90, v176, v90, v180
	v_sub_f32_e32 v91, v91, v192
	v_mul_f32_e32 v91, v91, v193
	v_fma_f32 v91, v177, v91, v181
	v_sub_f32_e32 v92, v92, v192
	v_mul_f32_e32 v92, v92, v193
	v_fma_f32 v92, v178, v92, v182
	v_sub_f32_e32 v93, v93, v192
	v_mul_f32_e32 v93, v93, v193
	v_fma_f32 v93, v179, v93, v183
	v_cvt_pk_bf16_f32 v152, v90, v91
	v_cvt_pk_bf16_f32 v153, v92, v93
	ds_read_b128 v[176:179], v136 offset:256
	ds_read_b128 v[180:183], v136 offset:4352
	s_waitcnt lgkmcnt(2)
	v_sub_f32_e32 v86, v86, v192
	v_mul_f32_e32 v86, v86, v193
	v_fma_f32 v86, v184, v86, v188
	v_sub_f32_e32 v87, v87, v192
	v_mul_f32_e32 v87, v87, v193
	v_fma_f32 v87, v185, v87, v189
	v_sub_f32_e32 v88, v88, v192
	v_mul_f32_e32 v88, v88, v193
	v_fma_f32 v88, v186, v88, v190
	v_sub_f32_e32 v89, v89, v192
	v_mul_f32_e32 v89, v89, v193
	v_fma_f32 v89, v187, v89, v191
	v_cvt_pk_bf16_f32 v154, v86, v87
	v_cvt_pk_bf16_f32 v155, v88, v89
	s_nop 1
	v_permlane16_swap_b32 v152, v154
	v_permlane16_swap_b32 v153, v155
	global_store_dwordx4 v137, v[152:155], s[94:95] sc1
	s_add_u32 s94, s94, 0x2000
	s_addc_u32 s95, s95, 0
	ds_read_b128 v[184:187], v136 offset:320
	ds_read_b128 v[188:191], v136 offset:4416
	s_waitcnt lgkmcnt(2)
	v_sub_f32_e32 v82, v82, v192
	v_mul_f32_e32 v82, v82, v193
	v_fma_f32 v82, v176, v82, v180
	v_sub_f32_e32 v83, v83, v192
	v_mul_f32_e32 v83, v83, v193
	v_fma_f32 v83, v177, v83, v181
	v_sub_f32_e32 v84, v84, v192
	v_mul_f32_e32 v84, v84, v193
	v_fma_f32 v84, v178, v84, v182
	v_sub_f32_e32 v85, v85, v192
	v_mul_f32_e32 v85, v85, v193
	v_fma_f32 v85, v179, v85, v183
	v_cvt_pk_bf16_f32 v144, v82, v83
	v_cvt_pk_bf16_f32 v145, v84, v85
	ds_read_b128 v[176:179], v136 offset:384
	ds_read_b128 v[180:183], v136 offset:4480
	s_waitcnt lgkmcnt(2)
	v_sub_f32_e32 v78, v78, v192
	v_mul_f32_e32 v78, v78, v193
	v_fma_f32 v78, v184, v78, v188
	v_sub_f32_e32 v79, v79, v192
	v_mul_f32_e32 v79, v79, v193
	v_fma_f32 v79, v185, v79, v189
	v_sub_f32_e32 v80, v80, v192
	v_mul_f32_e32 v80, v80, v193
	v_fma_f32 v80, v186, v80, v190
	v_sub_f32_e32 v81, v81, v192
	v_mul_f32_e32 v81, v81, v193
	v_fma_f32 v81, v187, v81, v191
	v_cvt_pk_bf16_f32 v146, v78, v79
	v_cvt_pk_bf16_f32 v147, v80, v81
	s_nop 1
	v_permlane16_swap_b32 v144, v146
	v_permlane16_swap_b32 v145, v147
	global_store_dwordx4 v137, v[144:147], s[94:95] sc1
	s_add_u32 s94, s94, 0x2000
	s_addc_u32 s95, s95, 0
	ds_read_b128 v[184:187], v136 offset:448
	ds_read_b128 v[188:191], v136 offset:4544
	s_waitcnt lgkmcnt(2)
	v_sub_f32_e32 v74, v74, v192
	v_mul_f32_e32 v74, v74, v193
	v_fma_f32 v74, v176, v74, v180
	v_sub_f32_e32 v75, v75, v192
	v_mul_f32_e32 v75, v75, v193
	v_fma_f32 v75, v177, v75, v181
	v_sub_f32_e32 v76, v76, v192
	v_mul_f32_e32 v76, v76, v193
	v_fma_f32 v76, v178, v76, v182
	v_sub_f32_e32 v77, v77, v192
	v_mul_f32_e32 v77, v77, v193
	v_fma_f32 v77, v179, v77, v183
	v_cvt_pk_bf16_f32 v152, v74, v75
	v_cvt_pk_bf16_f32 v153, v76, v77
	s_waitcnt lgkmcnt(0)
	v_sub_f32_e32 v70, v70, v192
	v_mul_f32_e32 v70, v70, v193
	v_fma_f32 v70, v184, v70, v188
	v_sub_f32_e32 v71, v71, v192
	v_mul_f32_e32 v71, v71, v193
	v_fma_f32 v71, v185, v71, v189
	v_sub_f32_e32 v72, v72, v192
	v_mul_f32_e32 v72, v72, v193
	v_fma_f32 v72, v186, v72, v190
	v_sub_f32_e32 v73, v73, v192
	v_mul_f32_e32 v73, v73, v193
	v_fma_f32 v73, v187, v73, v191
	v_cvt_pk_bf16_f32 v154, v70, v71
	v_cvt_pk_bf16_f32 v155, v72, v73
	s_nop 1
	v_permlane16_swap_b32 v152, v154
	v_permlane16_swap_b32 v153, v155
	global_store_dwordx4 v137, v[152:155], s[94:95] sc1
	s_waitcnt vmcnt(12) lgkmcnt(0)
	s_barrier
; DI float bf2f(unsigned b) { return __uint_as_float(b << 16); }
; DI void unit_O(const Params& p, char* lds, int l, int tile, int glu_tiles, int tile_b) {
;     ...
;         float s2[2], ss2[2];
; #pragma unroll
;         for (int mh = 0; mh < 2; ++mh) {
;             const int mt = half * 2 + mh, rl = mh * 16 + l15;
;             float s = 0.f, ss = 0.f;
; #pragma unroll
;             for (int nt = 0; nt < 8; ++nt) {
;                 f32x4 xr;
;                 if (l == 0) {
;                     const int chunk = wid * 32 + nt * 4 + quad;
;                     xr = *(const f32x4*)(XR + rl * 4096 + ((chunk ^ l15) << 4));
;                 } else {
;                     const u32x2 hb = *(const u32x2*)(XR + ((wid * 4 + (nt >> 1)) * 32 + rl) * 64 + (nt & 1) * 32 + quad * 8);
;                     xr = (f32x4){bf2f(hb[0] & 0xffffu), bf2f(hb[0] >> 16), bf2f(hb[1] & 0xffffu), bf2f(hb[1] >> 16)};
;                 }
; #pragma unroll
;                 for (int i = 0; i < 4; ++i) { const float v = acc[mt][nt][i] + DN_ALPHA * xr[i]; acc[mt][nt][i] = v; s += v; ss += v * v; }
;             }
;             s2[mh] = s; ss2[mh] = ss;
;         }
; #pragma unroll
;         for (int mh = 0; mh < 2; ++mh) { s2[mh] += __shfl_xor(s2[mh], 16); ss2[mh] += __shfl_xor(ss2[mh], 16); }
; #pragma unroll
;         for (int mh = 0; mh < 2; ++mh) { s2[mh] += __shfl_xor(s2[mh], 32); ss2[mh] += __shfl_xor(ss2[mh], 32); }
;         if (quad == 0) {
; #pragma unroll
;             for (int mh = 0; mh < 2; ++mh) *(f32x2*)&red[((mh * 16 + l15) * 8 + wid) * 2] = (f32x2){s2[mh], ss2[mh]};
;         }
;         __syncthreads();
;         if (half == 0) issue_x(1);
; #pragma unroll
;         for (int mh = 0; mh < 2; ++mh) {
;             const int mt = half * 2 + mh, rl = mh * 16 + l15, row = mt * 16 + l15;
;             float s = 0.f, ss = 0.f;
; #pragma unroll
;             for (int w = 0; w < 4; ++w) { const f32x4 v = *(const f32x4*)&red[rl * 16 + 4 * w]; s += v[0] + v[2]; ss += v[1] + v[3]; }
;             const float mu = s * (1.f / 1024.f);
;             const float var = ss * (1.f / 1024.f) - mu * mu;
;             const float rs = rsqrtf(var + LN_EPS);
	ds_read_b128 v[144:147], v204
	ds_read_b128 v[148:151], v205
	ds_read_b128 v[152:155], v206
	ds_read_b128 v[156:159], v207
	ds_read_b128 v[160:163], v204 offset:256
	ds_read_b128 v[164:167], v205 offset:256
	ds_read_b128 v[168:171], v206 offset:256
	ds_read_b128 v[172:175], v207 offset:256
	s_waitcnt lgkmcnt(7)
	v_fmac_f32_e32 v126, s58, v144
	v_fmac_f32_e32 v127, s58, v145
	v_fmac_f32_e32 v128, s58, v146
	v_fmac_f32_e32 v129, s58, v147
	v_mov_b32_e32 v196, v126
	v_mul_f32_e32 v197, v126, v126
	v_mov_b32_e32 v130, v127
	v_mul_f32_e32 v142, v127, v127
	v_add_f32_e32 v196, v196, v128
	v_fmac_f32_e32 v197, v128, v128
	v_add_f32_e32 v130, v130, v129
	v_fmac_f32_e32 v142, v129, v129
	s_waitcnt lgkmcnt(6)
	v_fmac_f32_e32 v122, s58, v148
	v_fmac_f32_e32 v123, s58, v149
	v_fmac_f32_e32 v124, s58, v150
	v_fmac_f32_e32 v125, s58, v151
	v_add_f32_e32 v196, v196, v122
	v_fmac_f32_e32 v197, v122, v122
	v_add_f32_e32 v130, v130, v123
	v_fmac_f32_e32 v142, v123, v123
	v_add_f32_e32 v196, v196, v124
	v_fmac_f32_e32 v197, v124, v124
	v_add_f32_e32 v130, v130, v125
	v_fmac_f32_e32 v142, v125, v125
	s_waitcnt lgkmcnt(5)
	v_fmac_f32_e32 v118, s58, v152
	v_fmac_f32_e32 v119, s58, v153
	v_fmac_f32_e32 v120, s58, v154
	v_fmac_f32_e32 v121, s58, v155
	v_add_f32_e32 v196, v196, v118
	v_fmac_f32_e32 v197, v118, v118
	v_add_f32_e32 v130, v130, v119
	v_fmac_f32_e32 v142, v119, v119
	v_add_f32_e32 v196, v196, v120
	v_fmac_f32_e32 v197, v120, v120
	v_add_f32_e32 v130, v130, v121
	v_fmac_f32_e32 v142, v121, v121
	s_waitcnt lgkmcnt(4)
	v_fmac_f32_e32 v114, s58, v156
	v_fmac_f32_e32 v115, s58, v157
	v_fmac_f32_e32 v116, s58, v158
	v_fmac_f32_e32 v117, s58, v159
	v_add_f32_e32 v196, v196, v114
	v_fmac_f32_e32 v197, v114, v114
	v_add_f32_e32 v130, v130, v115
	v_fmac_f32_e32 v142, v115, v115
	v_add_f32_e32 v196, v196, v116
	v_fmac_f32_e32 v197, v116, v116
	v_add_f32_e32 v130, v130, v117
	v_fmac_f32_e32 v142, v117, v117
	s_waitcnt lgkmcnt(3)
	v_fmac_f32_e32 v110, s58, v160
	v_fmac_f32_e32 v111, s58, v161
	v_fmac_f32_e32 v112, s58, v162
	v_fmac_f32_e32 v113, s58, v163
	v_add_f32_e32 v196, v196, v110
	v_fmac_f32_e32 v197, v110, v110
	v_add_f32_e32 v130, v130, v111
	v_fmac_f32_e32 v142, v111, v111
	v_add_f32_e32 v196, v196, v112
	v_fmac_f32_e32 v197, v112, v112
	v_add_f32_e32 v130, v130, v113
	v_fmac_f32_e32 v142, v113, v113
	s_waitcnt lgkmcnt(2)
	v_fmac_f32_e32 v106, s58, v164
	v_fmac_f32_e32 v107, s58, v165
	v_fmac_f32_e32 v108, s58, v166
	v_fmac_f32_e32 v109, s58, v167
	v_add_f32_e32 v196, v196, v106
	v_fmac_f32_e32 v197, v106, v106
	v_add_f32_e32 v130, v130, v107
	v_fmac_f32_e32 v142, v107, v107
	v_add_f32_e32 v196, v196, v108
	v_fmac_f32_e32 v197, v108, v108
	v_add_f32_e32 v130, v130, v109
	v_fmac_f32_e32 v142, v109, v109
	s_waitcnt lgkmcnt(1)
	v_fmac_f32_e32 v102, s58, v168
	v_fmac_f32_e32 v103, s58, v169
	v_fmac_f32_e32 v104, s58, v170
	v_fmac_f32_e32 v105, s58, v171
	v_add_f32_e32 v196, v196, v102
	v_fmac_f32_e32 v197, v102, v102
	v_add_f32_e32 v130, v130, v103
	v_fmac_f32_e32 v142, v103, v103
	v_add_f32_e32 v196, v196, v104
	v_fmac_f32_e32 v197, v104, v104
	v_add_f32_e32 v130, v130, v105
	v_fmac_f32_e32 v142, v105, v105
	s_waitcnt lgkmcnt(0)
	v_fmac_f32_e32 v66, s58, v172
	v_fmac_f32_e32 v67, s58, v173
	v_fmac_f32_e32 v68, s58, v174
	v_fmac_f32_e32 v69, s58, v175
	v_add_f32_e32 v196, v196, v66
	v_fmac_f32_e32 v197, v66, v66
	v_add_f32_e32 v130, v130, v67
	v_fmac_f32_e32 v142, v67, v67
	v_add_f32_e32 v196, v196, v68
	v_fmac_f32_e32 v197, v68, v68
	v_add_f32_e32 v130, v130, v69
	v_fmac_f32_e32 v142, v69, v69
	v_add_f32_e32 v196, v196, v130
	v_add_f32_e32 v197, v197, v142
	v_mov_b32_e32 v198, v196
	v_mov_b32_e32 v199, v197
	s_nop 1
	v_permlane16_swap_b32 v198, v196
	v_permlane16_swap_b32 v199, v197
	v_add_f32_e32 v196, v196, v198
	v_add_f32_e32 v197, v197, v199
	v_mov_b32_e32 v198, v196
	v_mov_b32_e32 v199, v197
	s_nop 1
	v_permlane32_swap_b32 v198, v196
	v_permlane32_swap_b32 v199, v197
	v_add_f32_e32 v196, v196, v198
	v_add_f32_e32 v197, v197, v199
	s_mov_b64 exec, 0xffff
	ds_write_b64 v134, v[196:197]
	s_mov_b64 exec, -1
	s_waitcnt lgkmcnt(0)
	s_barrier
	s_add_u32 s92, s96, 0x30000
	s_addc_u32 s93, s97, 0
	s_add_u32 s40, s91, 0x10000
	s_mov_b32 m0, s40
	s_nop 0
	global_load_lds_dwordx4 v208, s[92:93]
	global_load_lds_dwordx4 v208, s[92:93] offset:1024
	global_load_lds_dwordx4 v208, s[92:93] offset:2048
	global_load_lds_dwordx4 v208, s[92:93] offset:3072
	s_add_u32 s92, s96, 0x31000
	s_addc_u32 s93, s97, 0
	s_add_u32 s40, s91, 0x11000
	s_mov_b32 m0, s40
	s_nop 0
	global_load_lds_dwordx4 v209, s[92:93]
	global_load_lds_dwordx4 v209, s[92:93] offset:1024
	global_load_lds_dwordx4 v209, s[92:93] offset:2048
	global_load_lds_dwordx4 v209, s[92:93] offset:3072
	ds_read_b128 v[160:163], v135 offset:0
	ds_read_b128 v[164:167], v135 offset:16
	ds_read_b128 v[168:171], v135 offset:32
	ds_read_b128 v[172:175], v135 offset:48
	s_waitcnt lgkmcnt(0)
	v_add_f32_e32 v160, v160, v162
	v_add_f32_e32 v161, v161, v163
	v_add_f32_e32 v164, v164, v166
	v_add_f32_e32 v165, v165, v167
	v_add_f32_e32 v168, v168, v170
	v_add_f32_e32 v169, v169, v171
	v_add_f32_e32 v172, v172, v174
	v_add_f32_e32 v173, v173, v175
	v_add_f32_e32 v160, v160, v164
	v_add_f32_e32 v161, v161, v165
	v_add_f32_e32 v168, v168, v172
	v_add_f32_e32 v169, v169, v173
	v_add_f32_e32 v160, v160, v168
	v_add_f32_e32 v161, v161, v169
	v_mul_f32_e32 v192, 0x3a800000, v160
	v_mul_f32_e32 v193, 0x3a800000, v161
	v_fma_f32 v193, -v192, v192, v193
	v_add_f32_e32 v193, 0x3727c5ac, v193
	v_rsq_f32_e32 v193, v193
	s_nop 0
	s_add_u32 s94, s78, 0x400
	s_addc_u32 s95, s79, 0
	ds_read_b128 v[176:179], v136
	ds_read_b128 v[180:183], v136 offset:4096
	ds_read_b128 v[184:187], v136 offset:64
	ds_read_b128 v[188:191], v136 offset:4160
	s_waitcnt lgkmcnt(2)
; DI unsigned pk2(float lo, float hi) { const f32x2 v = {lo, hi}; const bf16x2_t b = __builtin_convertvector(v, bf16x2_t); return __builtin_bit_cast(unsigned, b); }
; DI size_t xb_off(int tok, int col) { return ((size_t)(((tok >> 7) * 32 + (col >> 5)) * 128 + (tok & 127))) * 32 + (col & 31); }
; DI void unit_O(const Params& p, char* lds, int l, int tile, int glu_tiles, int tile_b) {
;     ...
;             float* orow = xo + (r0 + row) * 1024 + wid * 128 + quad * 4;
;             bf16_t* brow = xbo + xb_off((int)r0 + row, wid * 128) + quad * 4;
;             const float* gp = GB + wid * 128 + quad * 4;
; #pragma unroll
;             for (int nt = 0; nt < 8; ++nt) {
;                 const f32x4 g = *(const f32x4*)(gp + nt * 16), bb = *(const f32x4*)(gp + 1024 + nt * 16);
;                 f32x4 o;
; #pragma unroll
;                 for (int i = 0; i < 4; ++i) o[i] = (acc[mt][nt][i] - mu) * rs * g[i] + bb[i];
;                 if (l == 0) *(u32x2*)(brow + (nt >> 1) * 4096 + (nt & 1) * 16) = (u32x2){pk2(o[0], o[1]), pk2(o[2], o[3])};
;                 else *(f32x4*)(orow + nt * 16) = o;
;             }
	v_sub_f32_e32 v126, v126, v192
	v_mul_f32_e32 v126, v126, v193
	v_fma_f32 v126, v176, v126, v180
	v_sub_f32_e32 v127, v127, v192
	v_mul_f32_e32 v127, v127, v193
	v_fma_f32 v127, v177, v127, v181
	v_sub_f32_e32 v128, v128, v192
	v_mul_f32_e32 v128, v128, v193
	v_fma_f32 v128, v178, v128, v182
	v_sub_f32_e32 v129, v129, v192
	v_mul_f32_e32 v129, v129, v193
	v_fma_f32 v129, v179, v129, v183
	v_cvt_pk_bf16_f32 v144, v126, v127
	v_cvt_pk_bf16_f32 v145, v128, v129
	ds_read_b128 v[176:179], v136 offset:128
	ds_read_b128 v[180:183], v136 offset:4224
	s_waitcnt lgkmcnt(2)
	v_sub_f32_e32 v122, v122, v192
	v_mul_f32_e32 v122, v122, v193
	v_fma_f32 v122, v184, v122, v188
	v_sub_f32_e32 v123, v123, v192
	v_mul_f32_e32 v123, v123, v193
	v_fma_f32 v123, v185, v123, v189
	v_sub_f32_e32 v124, v124, v192
	v_mul_f32_e32 v124, v124, v193
	v_fma_f32 v124, v186, v124, v190
	v_sub_f32_e32 v125, v125, v192
	v_mul_f32_e32 v125, v125, v193
	v_fma_f32 v125, v187, v125, v191
	v_cvt_pk_bf16_f32 v146, v122, v123
	v_cvt_pk_bf16_f32 v147, v124, v125
	s_nop 1
	v_permlane16_swap_b32 v144, v146
	v_permlane16_swap_b32 v145, v147
	global_store_dwordx4 v137, v[144:147], s[94:95] sc1
	s_add_u32 s94, s94, 0x2000
	s_addc_u32 s95, s95, 0
	ds_read_b128 v[184:187], v136 offset:192
	ds_read_b128 v[188:191], v136 offset:4288
	s_waitcnt lgkmcnt(2)
	v_sub_f32_e32 v118, v118, v192
	v_mul_f32_e32 v118, v118, v193
	v_fma_f32 v118, v176, v118, v180
	v_sub_f32_e32 v119, v119, v192
	v_mul_f32_e32 v119, v119, v193
	v_fma_f32 v119, v177, v119, v181
	v_sub_f32_e32 v120, v120, v192
	v_mul_f32_e32 v120, v120, v193
	v_fma_f32 v120, v178, v120, v182
	v_sub_f32_e32 v121, v121, v192
	v_mul_f32_e32 v121, v121, v193
	v_fma_f32 v121, v179, v121, v183
	v_cvt_pk_bf16_f32 v152, v118, v119
	v_cvt_pk_bf16_f32 v153, v120, v121
	ds_read_b128 v[176:179], v136 offset:256
	ds_read_b128 v[180:183], v136 offset:4352
	s_waitcnt lgkmcnt(2)
	v_sub_f32_e32 v114, v114, v192
	v_mul_f32_e32 v114, v114, v193
	v_fma_f32 v114, v184, v114, v188
	v_sub_f32_e32 v115, v115, v192
	v_mul_f32_e32 v115, v115, v193
	v_fma_f32 v115, v185, v115, v189
	v_sub_f32_e32 v116, v116, v192
	v_mul_f32_e32 v116, v116, v193
	v_fma_f32 v116, v186, v116, v190
	v_sub_f32_e32 v117, v117, v192
	v_mul_f32_e32 v117, v117, v193
	v_fma_f32 v117, v187, v117, v191
	v_cvt_pk_bf16_f32 v154, v114, v115
	v_cvt_pk_bf16_f32 v155, v116, v117
	s_nop 1
	v_permlane16_swap_b32 v152, v154
	v_permlane16_swap_b32 v153, v155
	global_store_dwordx4 v137, v[152:155], s[94:95] sc1
	s_add_u32 s94, s94, 0x2000
	s_addc_u32 s95, s95, 0
	ds_read_b128 v[184:187], v136 offset:320
	ds_read_b128 v[188:191], v136 offset:4416
	s_waitcnt lgkmcnt(2)
	v_sub_f32_e32 v110, v110, v192
	v_mul_f32_e32 v110, v110, v193
	v_fma_f32 v110, v176, v110, v180
	v_sub_f32_e32 v111, v111, v192
	v_mul_f32_e32 v111, v111, v193
	v_fma_f32 v111, v177, v111, v181
	v_sub_f32_e32 v112, v112, v192
	v_mul_f32_e32 v112, v112, v193
	v_fma_f32 v112, v178, v112, v182
	v_sub_f32_e32 v113, v113, v192
	v_mul_f32_e32 v113, v113, v193
	v_fma_f32 v113, v179, v113, v183
	v_cvt_pk_bf16_f32 v144, v110, v111
	v_cvt_pk_bf16_f32 v145, v112, v113
	ds_read_b128 v[176:179], v136 offset:384
	ds_read_b128 v[180:183], v136 offset:4480
	s_waitcnt lgkmcnt(2)
	v_sub_f32_e32 v106, v106, v192
	v_mul_f32_e32 v106, v106, v193
	v_fma_f32 v106, v184, v106, v188
	v_sub_f32_e32 v107, v107, v192
	v_mul_f32_e32 v107, v107, v193
	v_fma_f32 v107, v185, v107, v189
	v_sub_f32_e32 v108, v108, v192
	v_mul_f32_e32 v108, v108, v193
	v_fma_f32 v108, v186, v108, v190
	v_sub_f32_e32 v109, v109, v192
	v_mul_f32_e32 v109, v109, v193
	v_fma_f32 v109, v187, v109, v191
	v_cvt_pk_bf16_f32 v146, v106, v107
	v_cvt_pk_bf16_f32 v147, v108, v109
	s_nop 1
	v_permlane16_swap_b32 v144, v146
	v_permlane16_swap_b32 v145, v147
	global_store_dwordx4 v137, v[144:147], s[94:95] sc1
	s_add_u32 s94, s94, 0x2000
	s_addc_u32 s95, s95, 0
	ds_read_b128 v[184:187], v136 offset:448
	ds_read_b128 v[188:191], v136 offset:4544
	s_waitcnt lgkmcnt(2)
	v_sub_f32_e32 v102, v102, v192
	v_mul_f32_e32 v102, v102, v193
	v_fma_f32 v102, v176, v102, v180
	v_sub_f32_e32 v103, v103, v192
	v_mul_f32_e32 v103, v103, v193
	v_fma_f32 v103, v177, v103, v181
	v_sub_f32_e32 v104, v104, v192
	v_mul_f32_e32 v104, v104, v193
	v_fma_f32 v104, v178, v104, v182
	v_sub_f32_e32 v105, v105, v192
	v_mul_f32_e32 v105, v105, v193
	v_fma_f32 v105, v179, v105, v183
	v_cvt_pk_bf16_f32 v152, v102, v103
	v_cvt_pk_bf16_f32 v153, v104, v105
	s_waitcnt lgkmcnt(0)
	v_sub_f32_e32 v66, v66, v192
	v_mul_f32_e32 v66, v66, v193
	v_fma_f32 v66, v184, v66, v188
	v_sub_f32_e32 v67, v67, v192
	v_mul_f32_e32 v67, v67, v193
	v_fma_f32 v67, v185, v67, v189
	v_sub_f32_e32 v68, v68, v192
	v_mul_f32_e32 v68, v68, v193
	v_fma_f32 v68, v186, v68, v190
	v_sub_f32_e32 v69, v69, v192
	v_mul_f32_e32 v69, v69, v193
	v_fma_f32 v69, v187, v69, v191
	v_cvt_pk_bf16_f32 v154, v66, v67
	v_cvt_pk_bf16_f32 v155, v68, v69
	s_nop 1
	v_permlane16_swap_b32 v152, v154
	v_permlane16_swap_b32 v153, v155
	global_store_dwordx4 v137, v[152:155], s[94:95] sc1
	s_waitcnt vmcnt(16) lgkmcnt(0)
	s_barrier
; DI void unit_O(const Params& p, char* lds, int l, int tile, int glu_tiles, int tile_b) {
;     ...
;         float s2[2], ss2[2];
; #pragma unroll
;         for (int mh = 0; mh < 2; ++mh) {
;             const int mt = half * 2 + mh, rl = mh * 16 + l15;
;             float s = 0.f, ss = 0.f;
; #pragma unroll
;             for (int nt = 0; nt < 8; ++nt) {
;                 f32x4 xr;
;                 if (l == 0) {
;                     const int chunk = wid * 32 + nt * 4 + quad;
;                     xr = *(const f32x4*)(XR + rl * 4096 + ((chunk ^ l15) << 4));
;                 } else {
;                     const u32x2 hb = *(const u32x2*)(XR + ((wid * 4 + (nt >> 1)) * 32 + rl) * 64 + (nt & 1) * 32 + quad * 8);
;                     xr = (f32x4){bf2f(hb[0] & 0xffffu), bf2f(hb[0] >> 16), bf2f(hb[1] & 0xffffu), bf2f(hb[1] >> 16)};
;                 }
; #pragma unroll
;                 for (int i = 0; i < 4; ++i) { const float v = acc[mt][nt][i] + DN_ALPHA * xr[i]; acc[mt][nt][i] = v; s += v; ss += v * v; }
;             }
;             s2[mh] = s; ss2[mh] = ss;
;         }
; #pragma unroll
;         for (int mh = 0; mh < 2; ++mh) { s2[mh] += __shfl_xor(s2[mh], 16); ss2[mh] += __shfl_xor(ss2[mh], 16); }
; #pragma unroll
;         for (int mh = 0; mh < 2; ++mh) { s2[mh] += __shfl_xor(s2[mh], 32); ss2[mh] += __shfl_xor(ss2[mh], 32); }
;         if (quad == 0) {
; #pragma unroll
;             for (int mh = 0; mh < 2; ++mh) *(f32x2*)&red[((mh * 16 + l15) * 8 + wid) * 2] = (f32x2){s2[mh], ss2[mh]};
;         }
;         __syncthreads();
;         if (half == 0) issue_x(1);
; #pragma unroll
;         for (int mh = 0; mh < 2; ++mh) {
;             const int mt = half * 2 + mh, rl = mh * 16 + l15, row = mt * 16 + l15;
;             float s = 0.f, ss = 0.f;
; #pragma unroll
;             for (int w = 0; w < 4; ++w) { const f32x4 v = *(const f32x4*)&red[rl * 16 + 4 * w]; s += v[0] + v[2]; ss += v[1] + v[3]; }
;             const float mu = s * (1.f / 1024.f);
;             const float var = ss * (1.f / 1024.f) - mu * mu;
;             const float rs = rsqrtf(var + LN_EPS);
;             float* orow = xo + (r0 + row) * 1024 + wid * 128 + quad * 4;
;             bf16_t* brow = xbo + xb_off((int)r0 + row, wid * 128) + quad * 4;
;             const float* gp = GB + wid * 128 + quad * 4;
; #pragma unroll
;             for (int nt = 0; nt < 8; ++nt) {
	ds_read_b128 v[144:147], v200
	ds_read_b128 v[148:151], v201
	ds_read_b128 v[152:155], v202
	ds_read_b128 v[156:159], v203
	ds_read_b128 v[160:163], v200 offset:256
	ds_read_b128 v[164:167], v201 offset:256
	ds_read_b128 v[168:171], v202 offset:256
	ds_read_b128 v[172:175], v203 offset:256
	s_waitcnt lgkmcnt(7)
	v_fmac_f32_e32 v34, s58, v144
	v_fmac_f32_e32 v35, s58, v145
	v_fmac_f32_e32 v36, s58, v146
	v_fmac_f32_e32 v37, s58, v147
	v_mov_b32_e32 v196, v34
	v_mul_f32_e32 v197, v34, v34
	v_mov_b32_e32 v130, v35
	v_mul_f32_e32 v142, v35, v35
	v_add_f32_e32 v196, v196, v36
	v_fmac_f32_e32 v197, v36, v36
	v_add_f32_e32 v130, v130, v37
	v_fmac_f32_e32 v142, v37, v37
	s_waitcnt lgkmcnt(6)
	v_fmac_f32_e32 v30, s58, v148
	v_fmac_f32_e32 v31, s58, v149
	v_fmac_f32_e32 v32, s58, v150
	v_fmac_f32_e32 v33, s58, v151
	v_add_f32_e32 v196, v196, v30
	v_fmac_f32_e32 v197, v30, v30
	v_add_f32_e32 v130, v130, v31
	v_fmac_f32_e32 v142, v31, v31
	v_add_f32_e32 v196, v196, v32
	v_fmac_f32_e32 v197, v32, v32
	v_add_f32_e32 v130, v130, v33
	v_fmac_f32_e32 v142, v33, v33
	s_waitcnt lgkmcnt(5)
	v_fmac_f32_e32 v26, s58, v152
	v_fmac_f32_e32 v27, s58, v153
	v_fmac_f32_e32 v28, s58, v154
	v_fmac_f32_e32 v29, s58, v155
	v_add_f32_e32 v196, v196, v26
	v_fmac_f32_e32 v197, v26, v26
	v_add_f32_e32 v130, v130, v27
	v_fmac_f32_e32 v142, v27, v27
	v_add_f32_e32 v196, v196, v28
	v_fmac_f32_e32 v197, v28, v28
	v_add_f32_e32 v130, v130, v29
	v_fmac_f32_e32 v142, v29, v29
	s_waitcnt lgkmcnt(4)
	v_fmac_f32_e32 v22, s58, v156
	v_fmac_f32_e32 v23, s58, v157
	v_fmac_f32_e32 v24, s58, v158
	v_fmac_f32_e32 v25, s58, v159
	v_add_f32_e32 v196, v196, v22
	v_fmac_f32_e32 v197, v22, v22
	v_add_f32_e32 v130, v130, v23
	v_fmac_f32_e32 v142, v23, v23
	v_add_f32_e32 v196, v196, v24
	v_fmac_f32_e32 v197, v24, v24
	v_add_f32_e32 v130, v130, v25
	v_fmac_f32_e32 v142, v25, v25
	s_waitcnt lgkmcnt(3)
	v_fmac_f32_e32 v18, s58, v160
	v_fmac_f32_e32 v19, s58, v161
	v_fmac_f32_e32 v20, s58, v162
	v_fmac_f32_e32 v21, s58, v163
	v_add_f32_e32 v196, v196, v18
	v_fmac_f32_e32 v197, v18, v18
	v_add_f32_e32 v130, v130, v19
	v_fmac_f32_e32 v142, v19, v19
	v_add_f32_e32 v196, v196, v20
	v_fmac_f32_e32 v197, v20, v20
	v_add_f32_e32 v130, v130, v21
	v_fmac_f32_e32 v142, v21, v21
	s_waitcnt lgkmcnt(2)
	v_fmac_f32_e32 v14, s58, v164
	v_fmac_f32_e32 v15, s58, v165
	v_fmac_f32_e32 v16, s58, v166
	v_fmac_f32_e32 v17, s58, v167
	v_add_f32_e32 v196, v196, v14
	v_fmac_f32_e32 v197, v14, v14
	v_add_f32_e32 v130, v130, v15
	v_fmac_f32_e32 v142, v15, v15
	v_add_f32_e32 v196, v196, v16
	v_fmac_f32_e32 v197, v16, v16
	v_add_f32_e32 v130, v130, v17
	v_fmac_f32_e32 v142, v17, v17
	s_waitcnt lgkmcnt(1)
	v_fmac_f32_e32 v10, s58, v168
	v_fmac_f32_e32 v11, s58, v169
	v_fmac_f32_e32 v12, s58, v170
	v_fmac_f32_e32 v13, s58, v171
	v_add_f32_e32 v196, v196, v10
	v_fmac_f32_e32 v197, v10, v10
	v_add_f32_e32 v130, v130, v11
	v_fmac_f32_e32 v142, v11, v11
	v_add_f32_e32 v196, v196, v12
	v_fmac_f32_e32 v197, v12, v12
	v_add_f32_e32 v130, v130, v13
	v_fmac_f32_e32 v142, v13, v13
	s_waitcnt lgkmcnt(0)
	v_fmac_f32_e32 v6, s58, v172
	v_fmac_f32_e32 v7, s58, v173
	v_fmac_f32_e32 v8, s58, v174
	v_fmac_f32_e32 v9, s58, v175
	v_add_f32_e32 v196, v196, v6
	v_fmac_f32_e32 v197, v6, v6
	v_add_f32_e32 v130, v130, v7
	v_fmac_f32_e32 v142, v7, v7
	v_add_f32_e32 v196, v196, v8
	v_fmac_f32_e32 v197, v8, v8
	v_add_f32_e32 v130, v130, v9
	v_fmac_f32_e32 v142, v9, v9
	v_add_f32_e32 v196, v196, v130
	v_add_f32_e32 v197, v197, v142
	v_mov_b32_e32 v198, v196
	v_mov_b32_e32 v199, v197
	s_nop 1
	v_permlane16_swap_b32 v198, v196
	v_permlane16_swap_b32 v199, v197
	v_add_f32_e32 v196, v196, v198
	v_add_f32_e32 v197, v197, v199
	v_mov_b32_e32 v198, v196
	v_mov_b32_e32 v199, v197
	s_nop 1
	v_permlane32_swap_b32 v198, v196
	v_permlane32_swap_b32 v199, v197
	v_add_f32_e32 v196, v196, v198
	v_add_f32_e32 v197, v197, v199
	s_mov_b64 exec, 0xffff
	ds_write_b64 v134, v[196:197]
	s_mov_b64 exec, -1
	s_waitcnt lgkmcnt(0)
	s_barrier
	ds_read_b128 v[160:163], v135 offset:0
	ds_read_b128 v[164:167], v135 offset:16
	ds_read_b128 v[168:171], v135 offset:32
	ds_read_b128 v[172:175], v135 offset:48
	s_waitcnt lgkmcnt(0)
	v_add_f32_e32 v160, v160, v162
	v_add_f32_e32 v161, v161, v163
	v_add_f32_e32 v164, v164, v166
	v_add_f32_e32 v165, v165, v167
	v_add_f32_e32 v168, v168, v170
	v_add_f32_e32 v169, v169, v171
	v_add_f32_e32 v172, v172, v174
	v_add_f32_e32 v173, v173, v175
	v_add_f32_e32 v160, v160, v164
	v_add_f32_e32 v161, v161, v165
	v_add_f32_e32 v168, v168, v172
	v_add_f32_e32 v169, v169, v173
	v_add_f32_e32 v160, v160, v168
	v_add_f32_e32 v161, v161, v169
	v_mul_f32_e32 v192, 0x3a800000, v160
	v_mul_f32_e32 v193, 0x3a800000, v161
	v_fma_f32 v193, -v192, v192, v193
	v_add_f32_e32 v193, 0x3727c5ac, v193
	v_rsq_f32_e32 v193, v193
	s_nop 0
	s_add_u32 s94, s78, 0x800
	s_addc_u32 s95, s79, 0
	ds_read_b128 v[176:179], v136
	ds_read_b128 v[180:183], v136 offset:4096
	ds_read_b128 v[184:187], v136 offset:64
	ds_read_b128 v[188:191], v136 offset:4160
	s_waitcnt lgkmcnt(2)
	v_sub_f32_e32 v34, v34, v192
	v_mul_f32_e32 v34, v34, v193
	v_fma_f32 v34, v176, v34, v180
	v_sub_f32_e32 v35, v35, v192
	v_mul_f32_e32 v35, v35, v193
	v_fma_f32 v35, v177, v35, v181
	v_sub_f32_e32 v36, v36, v192
	v_mul_f32_e32 v36, v36, v193
	v_fma_f32 v36, v178, v36, v182
	v_sub_f32_e32 v37, v37, v192
	v_mul_f32_e32 v37, v37, v193
	v_fma_f32 v37, v179, v37, v183
	v_cvt_pk_bf16_f32 v144, v34, v35
	v_cvt_pk_bf16_f32 v145, v36, v37
	ds_read_b128 v[176:179], v136 offset:128
	ds_read_b128 v[180:183], v136 offset:4224
	s_waitcnt lgkmcnt(2)
; DI unsigned pk2(float lo, float hi) { const f32x2 v = {lo, hi}; const bf16x2_t b = __builtin_convertvector(v, bf16x2_t); return __builtin_bit_cast(unsigned, b); }
; DI void unit_O(const Params& p, char* lds, int l, int tile, int glu_tiles, int tile_b) {
;     ...
; #pragma unroll
;             for (int nt = 0; nt < 8; ++nt) {
;                 const f32x4 g = *(const f32x4*)(gp + nt * 16), bb = *(const f32x4*)(gp + 1024 + nt * 16);
;                 f32x4 o;
; #pragma unroll
;                 for (int i = 0; i < 4; ++i) o[i] = (acc[mt][nt][i] - mu) * rs * g[i] + bb[i];
;                 if (l == 0) *(u32x2*)(brow + (nt >> 1) * 4096 + (nt & 1) * 16) = (u32x2){pk2(o[0], o[1]), pk2(o[2], o[3])};
;                 else *(f32x4*)(orow + nt * 16) = o;
;             }
	v_sub_f32_e32 v30, v30, v192
	v_mul_f32_e32 v30, v30, v193
	v_fma_f32 v30, v184, v30, v188
	v_sub_f32_e32 v31, v31, v192
	v_mul_f32_e32 v31, v31, v193
	v_fma_f32 v31, v185, v31, v189
	v_sub_f32_e32 v32, v32, v192
	v_mul_f32_e32 v32, v32, v193
	v_fma_f32 v32, v186, v32, v190
	v_sub_f32_e32 v33, v33, v192
	v_mul_f32_e32 v33, v33, v193
	v_fma_f32 v33, v187, v33, v191
	v_cvt_pk_bf16_f32 v146, v30, v31
	v_cvt_pk_bf16_f32 v147, v32, v33
	s_nop 1
	v_permlane16_swap_b32 v144, v146
	v_permlane16_swap_b32 v145, v147
	global_store_dwordx4 v137, v[144:147], s[94:95] sc1
	s_add_u32 s94, s94, 0x2000
	s_addc_u32 s95, s95, 0
	ds_read_b128 v[184:187], v136 offset:192
	ds_read_b128 v[188:191], v136 offset:4288
	s_waitcnt lgkmcnt(2)
	v_sub_f32_e32 v26, v26, v192
	v_mul_f32_e32 v26, v26, v193
	v_fma_f32 v26, v176, v26, v180
	v_sub_f32_e32 v27, v27, v192
	v_mul_f32_e32 v27, v27, v193
	v_fma_f32 v27, v177, v27, v181
	v_sub_f32_e32 v28, v28, v192
	v_mul_f32_e32 v28, v28, v193
	v_fma_f32 v28, v178, v28, v182
	v_sub_f32_e32 v29, v29, v192
	v_mul_f32_e32 v29, v29, v193
	v_fma_f32 v29, v179, v29, v183
	v_cvt_pk_bf16_f32 v152, v26, v27
	v_cvt_pk_bf16_f32 v153, v28, v29
	ds_read_b128 v[176:179], v136 offset:256
	ds_read_b128 v[180:183], v136 offset:4352
	s_waitcnt lgkmcnt(2)
	v_sub_f32_e32 v22, v22, v192
	v_mul_f32_e32 v22, v22, v193
	v_fma_f32 v22, v184, v22, v188
	v_sub_f32_e32 v23, v23, v192
	v_mul_f32_e32 v23, v23, v193
	v_fma_f32 v23, v185, v23, v189
	v_sub_f32_e32 v24, v24, v192
	v_mul_f32_e32 v24, v24, v193
	v_fma_f32 v24, v186, v24, v190
	v_sub_f32_e32 v25, v25, v192
	v_mul_f32_e32 v25, v25, v193
	v_fma_f32 v25, v187, v25, v191
	v_cvt_pk_bf16_f32 v154, v22, v23
	v_cvt_pk_bf16_f32 v155, v24, v25
	s_nop 1
	v_permlane16_swap_b32 v152, v154
	v_permlane16_swap_b32 v153, v155
	global_store_dwordx4 v137, v[152:155], s[94:95] sc1
	s_add_u32 s94, s94, 0x2000
	s_addc_u32 s95, s95, 0
	ds_read_b128 v[184:187], v136 offset:320
	ds_read_b128 v[188:191], v136 offset:4416
	s_waitcnt lgkmcnt(2)
	v_sub_f32_e32 v18, v18, v192
	v_mul_f32_e32 v18, v18, v193
	v_fma_f32 v18, v176, v18, v180
	v_sub_f32_e32 v19, v19, v192
	v_mul_f32_e32 v19, v19, v193
	v_fma_f32 v19, v177, v19, v181
	v_sub_f32_e32 v20, v20, v192
	v_mul_f32_e32 v20, v20, v193
	v_fma_f32 v20, v178, v20, v182
	v_sub_f32_e32 v21, v21, v192
	v_mul_f32_e32 v21, v21, v193
	v_fma_f32 v21, v179, v21, v183
	v_cvt_pk_bf16_f32 v144, v18, v19
	v_cvt_pk_bf16_f32 v145, v20, v21
	ds_read_b128 v[176:179], v136 offset:384
	ds_read_b128 v[180:183], v136 offset:4480
	s_waitcnt lgkmcnt(2)
	v_sub_f32_e32 v14, v14, v192
	v_mul_f32_e32 v14, v14, v193
	v_fma_f32 v14, v184, v14, v188
	v_sub_f32_e32 v15, v15, v192
	v_mul_f32_e32 v15, v15, v193
	v_fma_f32 v15, v185, v15, v189
	v_sub_f32_e32 v16, v16, v192
	v_mul_f32_e32 v16, v16, v193
	v_fma_f32 v16, v186, v16, v190
	v_sub_f32_e32 v17, v17, v192
	v_mul_f32_e32 v17, v17, v193
	v_fma_f32 v17, v187, v17, v191
	v_cvt_pk_bf16_f32 v146, v14, v15
	v_cvt_pk_bf16_f32 v147, v16, v17
	s_nop 1
	v_permlane16_swap_b32 v144, v146
	v_permlane16_swap_b32 v145, v147
	global_store_dwordx4 v137, v[144:147], s[94:95] sc1
	s_add_u32 s94, s94, 0x2000
	s_addc_u32 s95, s95, 0
	ds_read_b128 v[184:187], v136 offset:448
	ds_read_b128 v[188:191], v136 offset:4544
	s_waitcnt lgkmcnt(2)
	v_sub_f32_e32 v10, v10, v192
	v_mul_f32_e32 v10, v10, v193
	v_fma_f32 v10, v176, v10, v180
	v_sub_f32_e32 v11, v11, v192
	v_mul_f32_e32 v11, v11, v193
	v_fma_f32 v11, v177, v11, v181
	v_sub_f32_e32 v12, v12, v192
	v_mul_f32_e32 v12, v12, v193
	v_fma_f32 v12, v178, v12, v182
	v_sub_f32_e32 v13, v13, v192
	v_mul_f32_e32 v13, v13, v193
	v_fma_f32 v13, v179, v13, v183
	v_cvt_pk_bf16_f32 v152, v10, v11
	v_cvt_pk_bf16_f32 v153, v12, v13
	s_waitcnt lgkmcnt(0)
	v_sub_f32_e32 v6, v6, v192
	v_mul_f32_e32 v6, v6, v193
	v_fma_f32 v6, v184, v6, v188
	v_sub_f32_e32 v7, v7, v192
	v_mul_f32_e32 v7, v7, v193
	v_fma_f32 v7, v185, v7, v189
	v_sub_f32_e32 v8, v8, v192
	v_mul_f32_e32 v8, v8, v193
	v_fma_f32 v8, v186, v8, v190
	v_sub_f32_e32 v9, v9, v192
	v_mul_f32_e32 v9, v9, v193
	v_fma_f32 v9, v187, v9, v191
	v_cvt_pk_bf16_f32 v154, v6, v7
	v_cvt_pk_bf16_f32 v155, v8, v9
	s_nop 1
	v_permlane16_swap_b32 v152, v154
	v_permlane16_swap_b32 v153, v155
	global_store_dwordx4 v137, v[152:155], s[94:95] sc1
	s_waitcnt vmcnt(8) lgkmcnt(0)
	s_barrier
; DI float bf2f(unsigned b) { return __uint_as_float(b << 16); }
; DI void unit_O(const Params& p, char* lds, int l, int tile, int glu_tiles, int tile_b) {
;     ...
;         float s2[2], ss2[2];
; #pragma unroll
;         for (int mh = 0; mh < 2; ++mh) {
;             const int mt = half * 2 + mh, rl = mh * 16 + l15;
;             float s = 0.f, ss = 0.f;
; #pragma unroll
;             for (int nt = 0; nt < 8; ++nt) {
;                 f32x4 xr;
;                 if (l == 0) {
;                     const int chunk = wid * 32 + nt * 4 + quad;
;                     xr = *(const f32x4*)(XR + rl * 4096 + ((chunk ^ l15) << 4));
;                 } else {
;                     const u32x2 hb = *(const u32x2*)(XR + ((wid * 4 + (nt >> 1)) * 32 + rl) * 64 + (nt & 1) * 32 + quad * 8);
;                     xr = (f32x4){bf2f(hb[0] & 0xffffu), bf2f(hb[0] >> 16), bf2f(hb[1] & 0xffffu), bf2f(hb[1] >> 16)};
;                 }
; #pragma unroll
;                 for (int i = 0; i < 4; ++i) { const float v = acc[mt][nt][i] + DN_ALPHA * xr[i]; acc[mt][nt][i] = v; s += v; ss += v * v; }
;             }
;             s2[mh] = s; ss2[mh] = ss;
;         }
; #pragma unroll
;         for (int mh = 0; mh < 2; ++mh) { s2[mh] += __shfl_xor(s2[mh], 16); ss2[mh] += __shfl_xor(ss2[mh], 16); }
; #pragma unroll
;         for (int mh = 0; mh < 2; ++mh) { s2[mh] += __shfl_xor(s2[mh], 32); ss2[mh] += __shfl_xor(ss2[mh], 32); }
;         if (quad == 0) {
; #pragma unroll
;             for (int mh = 0; mh < 2; ++mh) *(f32x2*)&red[((mh * 16 + l15) * 8 + wid) * 2] = (f32x2){s2[mh], ss2[mh]};
;         }
;         __syncthreads();
	ds_read_b128 v[144:147], v204
	ds_read_b128 v[148:151], v205
	ds_read_b128 v[152:155], v206
	ds_read_b128 v[156:159], v207
	ds_read_b128 v[160:163], v204 offset:256
	ds_read_b128 v[164:167], v205 offset:256
	ds_read_b128 v[168:171], v206 offset:256
	ds_read_b128 v[172:175], v207 offset:256
	s_waitcnt lgkmcnt(7)
	v_fmac_f32_e32 v62, s58, v144
	v_fmac_f32_e32 v63, s58, v145
	v_fmac_f32_e32 v64, s58, v146
	v_fmac_f32_e32 v65, s58, v147
	v_mov_b32_e32 v196, v62
	v_mul_f32_e32 v197, v62, v62
	v_mov_b32_e32 v130, v63
	v_mul_f32_e32 v142, v63, v63
	v_add_f32_e32 v196, v196, v64
	v_fmac_f32_e32 v197, v64, v64
	v_add_f32_e32 v130, v130, v65
	v_fmac_f32_e32 v142, v65, v65
	s_waitcnt lgkmcnt(6)
	v_fmac_f32_e32 v58, s58, v148
	v_fmac_f32_e32 v59, s58, v149
	v_fmac_f32_e32 v60, s58, v150
	v_fmac_f32_e32 v61, s58, v151
	v_add_f32_e32 v196, v196, v58
	v_fmac_f32_e32 v197, v58, v58
	v_add_f32_e32 v130, v130, v59
	v_fmac_f32_e32 v142, v59, v59
	v_add_f32_e32 v196, v196, v60
	v_fmac_f32_e32 v197, v60, v60
	v_add_f32_e32 v130, v130, v61
	v_fmac_f32_e32 v142, v61, v61
	s_waitcnt lgkmcnt(5)
	v_fmac_f32_e32 v54, s58, v152
	v_fmac_f32_e32 v55, s58, v153
	v_fmac_f32_e32 v56, s58, v154
	v_fmac_f32_e32 v57, s58, v155
	v_add_f32_e32 v196, v196, v54
	v_fmac_f32_e32 v197, v54, v54
	v_add_f32_e32 v130, v130, v55
	v_fmac_f32_e32 v142, v55, v55
	v_add_f32_e32 v196, v196, v56
	v_fmac_f32_e32 v197, v56, v56
	v_add_f32_e32 v130, v130, v57
	v_fmac_f32_e32 v142, v57, v57
	s_waitcnt lgkmcnt(4)
	v_fmac_f32_e32 v50, s58, v156
	v_fmac_f32_e32 v51, s58, v157
	v_fmac_f32_e32 v52, s58, v158
	v_fmac_f32_e32 v53, s58, v159
	v_add_f32_e32 v196, v196, v50
	v_fmac_f32_e32 v197, v50, v50
	v_add_f32_e32 v130, v130, v51
	v_fmac_f32_e32 v142, v51, v51
	v_add_f32_e32 v196, v196, v52
	v_fmac_f32_e32 v197, v52, v52
	v_add_f32_e32 v130, v130, v53
	v_fmac_f32_e32 v142, v53, v53
	s_waitcnt lgkmcnt(3)
	v_fmac_f32_e32 v46, s58, v160
	v_fmac_f32_e32 v47, s58, v161
	v_fmac_f32_e32 v48, s58, v162
	v_fmac_f32_e32 v49, s58, v163
	v_add_f32_e32 v196, v196, v46
	v_fmac_f32_e32 v197, v46, v46
	v_add_f32_e32 v130, v130, v47
	v_fmac_f32_e32 v142, v47, v47
	v_add_f32_e32 v196, v196, v48
	v_fmac_f32_e32 v197, v48, v48
	v_add_f32_e32 v130, v130, v49
	v_fmac_f32_e32 v142, v49, v49
	s_waitcnt lgkmcnt(2)
	v_fmac_f32_e32 v42, s58, v164
	v_fmac_f32_e32 v43, s58, v165
	v_fmac_f32_e32 v44, s58, v166
	v_fmac_f32_e32 v45, s58, v167
	v_add_f32_e32 v196, v196, v42
	v_fmac_f32_e32 v197, v42, v42
	v_add_f32_e32 v130, v130, v43
	v_fmac_f32_e32 v142, v43, v43
	v_add_f32_e32 v196, v196, v44
	v_fmac_f32_e32 v197, v44, v44
	v_add_f32_e32 v130, v130, v45
	v_fmac_f32_e32 v142, v45, v45
	s_waitcnt lgkmcnt(1)
	v_fmac_f32_e32 v38, s58, v168
	v_fmac_f32_e32 v39, s58, v169
	v_fmac_f32_e32 v40, s58, v170
	v_fmac_f32_e32 v41, s58, v171
	v_add_f32_e32 v196, v196, v38
	v_fmac_f32_e32 v197, v38, v38
	v_add_f32_e32 v130, v130, v39
	v_fmac_f32_e32 v142, v39, v39
	v_add_f32_e32 v196, v196, v40
	v_fmac_f32_e32 v197, v40, v40
	v_add_f32_e32 v130, v130, v41
	v_fmac_f32_e32 v142, v41, v41
	s_waitcnt lgkmcnt(0)
	v_fmac_f32_e32 v2, s58, v172
	v_fmac_f32_e32 v3, s58, v173
	v_fmac_f32_e32 v4, s58, v174
	v_fmac_f32_e32 v5, s58, v175
	v_add_f32_e32 v196, v196, v2
	v_fmac_f32_e32 v197, v2, v2
	v_add_f32_e32 v130, v130, v3
	v_fmac_f32_e32 v142, v3, v3
	v_add_f32_e32 v196, v196, v4
	v_fmac_f32_e32 v197, v4, v4
	v_add_f32_e32 v130, v130, v5
	v_fmac_f32_e32 v142, v5, v5
	v_add_f32_e32 v196, v196, v130
	v_add_f32_e32 v197, v197, v142
	v_mov_b32_e32 v198, v196
	v_mov_b32_e32 v199, v197
	s_nop 1
	v_permlane16_swap_b32 v198, v196
	v_permlane16_swap_b32 v199, v197
	v_add_f32_e32 v196, v196, v198
	v_add_f32_e32 v197, v197, v199
	v_mov_b32_e32 v198, v196
	v_mov_b32_e32 v199, v197
	s_nop 1
	v_permlane32_swap_b32 v198, v196
	v_permlane32_swap_b32 v199, v197
	v_add_f32_e32 v196, v196, v198
	v_add_f32_e32 v197, v197, v199
	s_mov_b64 exec, 0xffff
	ds_write_b64 v134, v[196:197]
	s_mov_b64 exec, -1
	s_waitcnt lgkmcnt(0)
	s_barrier
; DI unsigned pk2(float lo, float hi) { const f32x2 v = {lo, hi}; const bf16x2_t b = __builtin_convertvector(v, bf16x2_t); return __builtin_bit_cast(unsigned, b); }
; DI size_t xb_off(int tok, int col) { return ((size_t)(((tok >> 7) * 32 + (col >> 5)) * 128 + (tok & 127))) * 32 + (col & 31); }
; DI void unit_O(const Params& p, char* lds, int l, int tile, int glu_tiles, int tile_b) {
;     ...
; #pragma unroll
;         for (int mh = 0; mh < 2; ++mh) {
;             const int mt = half * 2 + mh, rl = mh * 16 + l15, row = mt * 16 + l15;
;             float s = 0.f, ss = 0.f;
; #pragma unroll
;             for (int w = 0; w < 4; ++w) { const f32x4 v = *(const f32x4*)&red[rl * 16 + 4 * w]; s += v[0] + v[2]; ss += v[1] + v[3]; }
;             const float mu = s * (1.f / 1024.f);
;             const float var = ss * (1.f / 1024.f) - mu * mu;
;             const float rs = rsqrtf(var + LN_EPS);
;             float* orow = xo + (r0 + row) * 1024 + wid * 128 + quad * 4;
;             bf16_t* brow = xbo + xb_off((int)r0 + row, wid * 128) + quad * 4;
;             const float* gp = GB + wid * 128 + quad * 4;
; #pragma unroll
;             for (int nt = 0; nt < 8; ++nt) {
;                 const f32x4 g = *(const f32x4*)(gp + nt * 16), bb = *(const f32x4*)(gp + 1024 + nt * 16);
;                 f32x4 o;
; #pragma unroll
;                 for (int i = 0; i < 4; ++i) o[i] = (acc[mt][nt][i] - mu) * rs * g[i] + bb[i];
;                 if (l == 0) *(u32x2*)(brow + (nt >> 1) * 4096 + (nt & 1) * 16) = (u32x2){pk2(o[0], o[1]), pk2(o[2], o[3])};
;                 else *(f32x4*)(orow + nt * 16) = o;
;             }
	ds_read_b128 v[160:163], v135 offset:0
	ds_read_b128 v[164:167], v135 offset:16
	ds_read_b128 v[168:171], v135 offset:32
	ds_read_b128 v[172:175], v135 offset:48
	s_waitcnt lgkmcnt(0)
	v_add_f32_e32 v160, v160, v162
	v_add_f32_e32 v161, v161, v163
	v_add_f32_e32 v164, v164, v166
	v_add_f32_e32 v165, v165, v167
	v_add_f32_e32 v168, v168, v170
	v_add_f32_e32 v169, v169, v171
	v_add_f32_e32 v172, v172, v174
	v_add_f32_e32 v173, v173, v175
	v_add_f32_e32 v160, v160, v164
	v_add_f32_e32 v161, v161, v165
	v_add_f32_e32 v168, v168, v172
	v_add_f32_e32 v169, v169, v173
	v_add_f32_e32 v160, v160, v168
	v_add_f32_e32 v161, v161, v169
	v_mul_f32_e32 v192, 0x3a800000, v160
	v_mul_f32_e32 v193, 0x3a800000, v161
	v_fma_f32 v193, -v192, v192, v193
	v_add_f32_e32 v193, 0x3727c5ac, v193
	v_rsq_f32_e32 v193, v193
	s_nop 0
	s_add_u32 s94, s78, 0xc00
	s_addc_u32 s95, s79, 0
	ds_read_b128 v[176:179], v136
	ds_read_b128 v[180:183], v136 offset:4096
	ds_read_b128 v[184:187], v136 offset:64
	ds_read_b128 v[188:191], v136 offset:4160
	s_waitcnt lgkmcnt(2)
	v_sub_f32_e32 v62, v62, v192
	v_mul_f32_e32 v62, v62, v193
	v_fma_f32 v62, v176, v62, v180
	v_sub_f32_e32 v63, v63, v192
	v_mul_f32_e32 v63, v63, v193
	v_fma_f32 v63, v177, v63, v181
	v_sub_f32_e32 v64, v64, v192
	v_mul_f32_e32 v64, v64, v193
	v_fma_f32 v64, v178, v64, v182
	v_sub_f32_e32 v65, v65, v192
	v_mul_f32_e32 v65, v65, v193
	v_fma_f32 v65, v179, v65, v183
	v_cvt_pk_bf16_f32 v144, v62, v63
	v_cvt_pk_bf16_f32 v145, v64, v65
	ds_read_b128 v[176:179], v136 offset:128
	ds_read_b128 v[180:183], v136 offset:4224
	s_waitcnt lgkmcnt(2)
	v_sub_f32_e32 v58, v58, v192
	v_mul_f32_e32 v58, v58, v193
	v_fma_f32 v58, v184, v58, v188
	v_sub_f32_e32 v59, v59, v192
	v_mul_f32_e32 v59, v59, v193
	v_fma_f32 v59, v185, v59, v189
	v_sub_f32_e32 v60, v60, v192
	v_mul_f32_e32 v60, v60, v193
	v_fma_f32 v60, v186, v60, v190
	v_sub_f32_e32 v61, v61, v192
	v_mul_f32_e32 v61, v61, v193
	v_fma_f32 v61, v187, v61, v191
	v_cvt_pk_bf16_f32 v146, v58, v59
	v_cvt_pk_bf16_f32 v147, v60, v61
	s_nop 1
	v_permlane16_swap_b32 v144, v146
	v_permlane16_swap_b32 v145, v147
	global_store_dwordx4 v137, v[144:147], s[94:95] sc1
	s_add_u32 s94, s94, 0x2000
	s_addc_u32 s95, s95, 0
	ds_read_b128 v[184:187], v136 offset:192
	ds_read_b128 v[188:191], v136 offset:4288
	s_waitcnt lgkmcnt(2)
	v_sub_f32_e32 v54, v54, v192
	v_mul_f32_e32 v54, v54, v193
	v_fma_f32 v54, v176, v54, v180
	v_sub_f32_e32 v55, v55, v192
	v_mul_f32_e32 v55, v55, v193
	v_fma_f32 v55, v177, v55, v181
	v_sub_f32_e32 v56, v56, v192
	v_mul_f32_e32 v56, v56, v193
	v_fma_f32 v56, v178, v56, v182
	v_sub_f32_e32 v57, v57, v192
	v_mul_f32_e32 v57, v57, v193
	v_fma_f32 v57, v179, v57, v183
	v_cvt_pk_bf16_f32 v152, v54, v55
	v_cvt_pk_bf16_f32 v153, v56, v57
	ds_read_b128 v[176:179], v136 offset:256
	ds_read_b128 v[180:183], v136 offset:4352
	s_waitcnt lgkmcnt(2)
	v_sub_f32_e32 v50, v50, v192
	v_mul_f32_e32 v50, v50, v193
	v_fma_f32 v50, v184, v50, v188
	v_sub_f32_e32 v51, v51, v192
	v_mul_f32_e32 v51, v51, v193
	v_fma_f32 v51, v185, v51, v189
	v_sub_f32_e32 v52, v52, v192
	v_mul_f32_e32 v52, v52, v193
	v_fma_f32 v52, v186, v52, v190
	v_sub_f32_e32 v53, v53, v192
	v_mul_f32_e32 v53, v53, v193
	v_fma_f32 v53, v187, v53, v191
	v_cvt_pk_bf16_f32 v154, v50, v51
	v_cvt_pk_bf16_f32 v155, v52, v53
	s_nop 1
	v_permlane16_swap_b32 v152, v154
	v_permlane16_swap_b32 v153, v155
	global_store_dwordx4 v137, v[152:155], s[94:95] sc1
	s_add_u32 s94, s94, 0x2000
	s_addc_u32 s95, s95, 0
	ds_read_b128 v[184:187], v136 offset:320
	ds_read_b128 v[188:191], v136 offset:4416
	s_waitcnt lgkmcnt(2)
	v_sub_f32_e32 v46, v46, v192
	v_mul_f32_e32 v46, v46, v193
	v_fma_f32 v46, v176, v46, v180
	v_sub_f32_e32 v47, v47, v192
	v_mul_f32_e32 v47, v47, v193
	v_fma_f32 v47, v177, v47, v181
	v_sub_f32_e32 v48, v48, v192
	v_mul_f32_e32 v48, v48, v193
	v_fma_f32 v48, v178, v48, v182
	v_sub_f32_e32 v49, v49, v192
	v_mul_f32_e32 v49, v49, v193
	v_fma_f32 v49, v179, v49, v183
	v_cvt_pk_bf16_f32 v144, v46, v47
	v_cvt_pk_bf16_f32 v145, v48, v49
	ds_read_b128 v[176:179], v136 offset:384
	ds_read_b128 v[180:183], v136 offset:4480
	s_waitcnt lgkmcnt(2)
	v_sub_f32_e32 v42, v42, v192
	v_mul_f32_e32 v42, v42, v193
	v_fma_f32 v42, v184, v42, v188
	v_sub_f32_e32 v43, v43, v192
	v_mul_f32_e32 v43, v43, v193
	v_fma_f32 v43, v185, v43, v189
	v_sub_f32_e32 v44, v44, v192
	v_mul_f32_e32 v44, v44, v193
	v_fma_f32 v44, v186, v44, v190
	v_sub_f32_e32 v45, v45, v192
	v_mul_f32_e32 v45, v45, v193
	v_fma_f32 v45, v187, v45, v191
	v_cvt_pk_bf16_f32 v146, v42, v43
	v_cvt_pk_bf16_f32 v147, v44, v45
	s_nop 1
	v_permlane16_swap_b32 v144, v146
	v_permlane16_swap_b32 v145, v147
	global_store_dwordx4 v137, v[144:147], s[94:95] sc1
	s_add_u32 s94, s94, 0x2000
	s_addc_u32 s95, s95, 0
	ds_read_b128 v[184:187], v136 offset:448
	ds_read_b128 v[188:191], v136 offset:4544
	s_waitcnt lgkmcnt(2)
	v_sub_f32_e32 v38, v38, v192
	v_mul_f32_e32 v38, v38, v193
	v_fma_f32 v38, v176, v38, v180
	v_sub_f32_e32 v39, v39, v192
	v_mul_f32_e32 v39, v39, v193
	v_fma_f32 v39, v177, v39, v181
	v_sub_f32_e32 v40, v40, v192
	v_mul_f32_e32 v40, v40, v193
	v_fma_f32 v40, v178, v40, v182
	v_sub_f32_e32 v41, v41, v192
	v_mul_f32_e32 v41, v41, v193
	v_fma_f32 v41, v179, v41, v183
	v_cvt_pk_bf16_f32 v152, v38, v39
	v_cvt_pk_bf16_f32 v153, v40, v41
	s_waitcnt lgkmcnt(0)
	v_sub_f32_e32 v2, v2, v192
	v_mul_f32_e32 v2, v2, v193
	v_fma_f32 v2, v184, v2, v188
	v_sub_f32_e32 v3, v3, v192
	v_mul_f32_e32 v3, v3, v193
	v_fma_f32 v3, v185, v3, v189
	v_sub_f32_e32 v4, v4, v192
	v_mul_f32_e32 v4, v4, v193
	v_fma_f32 v4, v186, v4, v190
	v_sub_f32_e32 v5, v5, v192
	v_mul_f32_e32 v5, v5, v193
	v_fma_f32 v5, v187, v5, v191
	v_cvt_pk_bf16_f32 v154, v2, v3
	v_cvt_pk_bf16_f32 v155, v4, v5
	s_nop 1
	v_permlane16_swap_b32 v152, v154
	v_permlane16_swap_b32 v153, v155
	global_store_dwordx4 v137, v[152:155], s[94:95] sc1
	s_branch .Le2_done
